# P3: s_setprio 3 for attention waves (reset at phase end); with barrier edits + P2 plain stores
# speedup vs baseline: 1.0009x; 1.0009x over previous
; #define AT_LDK(KF, RSX, i) do { const LAS unsigned char* kb_ = lds + KRING_OFF + (((RSX) + (i)) % 9) * 8192 + kc0 * 128; \
;                         _Pragma("unroll") for (int cbk = 0; cbk < 2; ++cbk) { KF[cbk][0] = *(const LAS bf16x8*)(kb_ + cbk * 2048 + koff0); KF[cbk][1] = *(const LAS bf16x8*)(kb_ + cbk * 2048 + koff1); } } while (0)
; #define AT_MF(KF) do { _Pragma("unroll") for (int cbk = 0; cbk < 2; ++cbk) { cq[cbk] = (f32x4){0.f, 0.f, 0.f, 0.f}; \
;                         cq[cbk] = __builtin_amdgcn_mfma_f32_16x16x32_bf16(KF[cbk][0], qfn[0], cq[cbk], 0, 0, 0); cq[cbk] = __builtin_amdgcn_mfma_f32_16x16x32_bf16(KF[cbk][1], qfn[1], cq[cbk], 0, 0, 0); } } while (0)
; #define AT_SC(RK, BS, i) do { f32x4 s_; _Pragma("unroll") for (int e = 0; e < 4; ++e) s_[e] = (sel[e] ? cq[1][e] : cq[0][e]) * (sel[e] ? RK[1][e] : RK[0][e]) + BS[e]; \
;                         sc[i] = s_; mxn = fmaxf(fmaxf(mxn, fmaxf(s_[0], s_[1])), fmaxf(s_[2], s_[3])); } while (0)
; __global__ void __launch_bounds__(NWAVES * 64, 2) fwd(Args a) {
;     ...
;                     if (st == 0) {
;                         AT_BUILDQ(qfn, qraw, qss); mxn = -3e38f;
;                         qss = hss[(size_t)h * MT + qrow + 64]; qraw[0] = *(const v4u*)(PROJg + (size_t)(qrow + 64 - GROWS * grp) * INW + h * 64 + 8 * fq); qraw[1] = *(const v4u*)(PROJg + (size_t)(qrow + 64 - GROWS * grp) * INW + h * 64 + 32 + 8 * fq);
;                         AT_LDK(kA, rs, 0);
; #pragma unroll
;                         for (int i2 = 0; i2 < 3; ++i2) {
;                             AT_LDK(kB, rs, 2 * i2 + 1); AT_LDRB(rkvA, bsvA, rs, tba, 2 * i2); __builtin_amdgcn_sched_barrier(0);
;                             AT_MF(kA); __builtin_amdgcn_sched_barrier(0); AT_SC(rkvA, bsvA, 2 * i2); __builtin_amdgcn_sched_barrier(0);
;                             AT_LDK(kA, rs, 2 * i2 + 2); AT_LDRB(rkvA, bsvA, rs, tba, 2 * i2 + 1); __builtin_amdgcn_sched_barrier(0);
;                             AT_MF(kB); __builtin_amdgcn_sched_barrier(0); AT_SC(rkvA, bsvA, 2 * i2 + 1); __builtin_amdgcn_sched_barrier(0);
;                         }
;                         AT_LDRB(rkvA, bsvA, rs, tba, 6); __builtin_amdgcn_sched_barrier(0);
;                         AT_MF(kA); __builtin_amdgcn_sched_barrier(0); AT_SC(rkvA, bsvA, 6); __builtin_amdgcn_sched_barrier(0);
.LBB0_375:
	s_setprio 3
	s_max_i32 s28, s85, 4
	s_add_i32 s28, s28, -4
	s_min_i32 s28, s84, s28
	s_add_i32 s28, s28, s93
	s_lshl_b32 s28, s28, 7
	s_add_i32 s28, s28, 0
	s_add_i32 s28, s28, 0x24000
	v_add_u32_e32 v90, s87, v139
	s_andn2_b64 vcc, exec, s[70:71]
	s_mul_hi_u32 s43, s41, 0x38e38e39
	v_add_u32_e32 v2, s28, v176
	v_add_u32_e32 v34, s28, v177
	v_add_u32_e32 v35, s28, v178
	v_add_u32_e32 v36, s28, v179
	v_add_u32_e32 v92, 0x25100, v192
	s_cbranch_vccnz .LBB0_377
	v_add_u32_e32 v8, 64, v137
	v_ashrrev_i32_e32 v91, 31, v90
	v_ashrrev_i32_e32 v9, 31, v8
	v_lshl_add_u64 v[6:7], v[90:91], 2, s[54:55]
	v_lshlrev_b64 v[8:9], 12, v[8:9]
	s_waitcnt vmcnt(0)
	v_fmamk_f32 v10, v194, 0x3c800000, v191
	v_lshlrev_b32_e32 v14, 16, v70
	v_and_b32_e32 v15, 0xffff0000, v70
	v_lshlrev_b32_e32 v16, 16, v71
	v_and_b32_e32 v17, 0xffff0000, v71
	v_lshlrev_b32_e32 v18, 16, v72
	v_and_b32_e32 v19, 0xffff0000, v72
	v_lshlrev_b32_e32 v20, 16, v73
	v_and_b32_e32 v21, 0xffff0000, v73
	v_lshlrev_b32_e32 v22, 16, v66
	v_and_b32_e32 v23, 0xffff0000, v66
	v_lshlrev_b32_e32 v24, 16, v67
	v_and_b32_e32 v25, 0xffff0000, v67
	v_lshlrev_b32_e32 v26, 16, v68
	v_and_b32_e32 v27, 0xffff0000, v68
	v_lshlrev_b32_e32 v54, 16, v69
	v_and_b32_e32 v55, 0xffff0000, v69
	v_lshl_add_u64 v[8:9], v[144:145], 0, v[8:9]
	global_load_dword v194, v[6:7], off offset:256
	global_load_dwordx4 v[70:73], v[8:9], off
	global_load_dwordx4 v[66:69], v[8:9], off offset:64
	v_mul_f32_e32 v6, 0x4b800000, v10
	v_cmp_gt_f32_e32 vcc, s14, v10
	s_lshr_b32 s28, s43, 1
	s_mul_i32 s28, s28, 9
	v_cndmask_b32_e32 v6, v10, v6, vcc
	v_rsq_f32_e32 v28, v6
	ds_read_b128 v[6:9], v92
	ds_read_b128 v[10:13], v92 offset:16
	s_sub_i32 s28, s41, s28
	v_mul_f32_e32 v29, 0x45800000, v28
	v_cndmask_b32_e32 v28, v28, v29, vcc
	v_mul_f32_e32 v28, 0x3e000000, v28
	s_waitcnt lgkmcnt(0)
	v_pk_mul_f32 v[6:7], v[28:29], v[6:7] op_sel_hi:[0,1]
	v_pk_mul_f32 v[8:9], v[28:29], v[8:9] op_sel_hi:[0,1]
	v_pk_mul_f32 v[6:7], v[6:7], v[14:15]
	v_pk_mul_f32 v[10:11], v[28:29], v[10:11] op_sel_hi:[0,1]
	v_cvt_pk_bf16_f32 v74, v6, v7
	v_pk_mul_f32 v[6:7], v[8:9], v[16:17]
	v_pk_mul_f32 v[10:11], v[10:11], v[18:19]
	v_cvt_pk_bf16_f32 v75, v6, v7
	ds_read_b128 v[6:9], v92 offset:128
	v_pk_mul_f32 v[30:31], v[28:29], v[12:13] op_sel_hi:[0,1]
	v_cvt_pk_bf16_f32 v76, v10, v11
	ds_read_b128 v[10:13], v92 offset:144
	s_lshl_b32 s70, s28, 13
	s_waitcnt lgkmcnt(1)
	v_pk_mul_f32 v[6:7], v[28:29], v[6:7] op_sel_hi:[0,1]
	v_pk_mul_f32 v[8:9], v[28:29], v[8:9] op_sel_hi:[0,1]
	v_pk_mul_f32 v[6:7], v[6:7], v[22:23]
	s_add_i32 s70, s89, s70
	v_cvt_pk_bf16_f32 v78, v6, v7
	v_pk_mul_f32 v[6:7], v[8:9], v[24:25]
	v_pk_mul_f32 v[14:15], v[30:31], v[20:21]
	v_cvt_pk_bf16_f32 v79, v6, v7
	v_add_u32_e32 v6, s70, v169
	v_add_u32_e32 v7, s70, v170
	s_or_b32 s70, s41, 1
	s_mul_hi_u32 s71, s70, 0x38e38e39
	s_lshr_b32 s71, s71, 1
	s_mul_i32 s71, s71, 9
	s_sub_i32 s70, s70, s71
	s_lshl_b32 s71, s70, 13
	s_waitcnt lgkmcnt(0)
	v_pk_mul_f32 v[10:11], v[28:29], v[10:11] op_sel_hi:[0,1]
	s_add_i32 s71, s89, s71
	v_cvt_pk_bf16_f32 v77, v14, v15
	v_pk_mul_f32 v[56:57], v[28:29], v[12:13] op_sel_hi:[0,1]
	v_pk_mul_f32 v[58:59], v[10:11], v[26:27]
	ds_read_b128 v[10:13], v6
	ds_read_b128 v[14:17], v6 offset:2048
	ds_read_b128 v[18:21], v7
	ds_read_b128 v[22:25], v7 offset:2048
	v_add_u32_e32 v6, s71, v169
	v_add_u32_e32 v7, s71, v170
	ds_read_b128 v[26:29], v6
	ds_read_b128 v[30:33], v6 offset:2048
	ds_read_b128 v[38:41], v7
	ds_read_b128 v[42:45], v7 offset:2048
	v_lshl_add_u32 v6, s28, 8, v175
	ds_read_b128 v[46:49], v6
	ds_read_b128 v[50:53], v6 offset:64
	ds_read_b32 v6, v2 offset:956
	ds_read_b32 v7, v34 offset:956
	ds_read_b32 v8, v35 offset:956
	ds_read_b32 v9, v36 offset:956
	v_pk_mul_f32 v[54:55], v[56:57], v[54:55]
	v_cvt_pk_bf16_f32 v80, v58, v59
	v_cvt_pk_bf16_f32 v81, v54, v55
	s_or_b32 s28, s41, 2
	s_waitcnt lgkmcnt(13)
	v_mfma_f32_16x16x32_bf16 v[10:13], v[10:13], v[74:77], 0
	s_waitcnt lgkmcnt(12)
	v_mfma_f32_16x16x32_bf16 v[14:17], v[14:17], v[74:77], 0
	s_waitcnt lgkmcnt(11)
	v_mfma_f32_16x16x32_bf16 v[10:13], v[18:21], v[78:81], v[10:13]
	s_waitcnt lgkmcnt(10)
	v_mfma_f32_16x16x32_bf16 v[14:17], v[22:25], v[78:81], v[14:17]
	s_nop 7
	v_cndmask_b32_e64 v10, v10, v14, s[4:5]
	s_waitcnt lgkmcnt(4)
	v_cndmask_b32_e64 v14, v46, v50, s[4:5]
	s_waitcnt lgkmcnt(3)
	v_fmac_f32_e32 v6, v10, v14
	v_cndmask_b32_e64 v10, v11, v15, s[6:7]
	v_cndmask_b32_e64 v11, v47, v51, s[6:7]
	s_waitcnt lgkmcnt(2)
	v_fmac_f32_e32 v7, v10, v11
	v_cndmask_b32_e64 v10, v12, v16, s[8:9]
	v_cndmask_b32_e64 v11, v48, v52, s[8:9]
	s_waitcnt lgkmcnt(1)
	v_fmac_f32_e32 v8, v10, v11
	v_cndmask_b32_e64 v10, v13, v17, s[10:11]
	v_cndmask_b32_e64 v11, v49, v53, s[10:11]
	s_waitcnt lgkmcnt(0)
	v_fmac_f32_e32 v9, v10, v11
	v_max_f32_e32 v37, v6, v7
	v_max_f32_e32 v58, v8, v9
	s_mul_hi_u32 s71, s28, 0x38e38e39
	s_lshr_b32 s71, s71, 1
	s_mul_i32 s71, s71, 9
	s_sub_i32 s28, s28, s71
	s_lshl_b32 s71, s28, 13
	s_add_i32 s71, s89, s71
	v_add_u32_e32 v10, s71, v169
	v_add_u32_e32 v11, s71, v170
	ds_read_b128 v[18:21], v10
	ds_read_b128 v[22:25], v10 offset:2048
	ds_read_b128 v[46:49], v11
	ds_read_b128 v[50:53], v11 offset:2048
	v_lshl_add_u32 v10, s70, 8, v175
	ds_read_b128 v[14:17], v10
	ds_read_b128 v[54:57], v10 offset:64
	ds_read_b32 v10, v2 offset:1084
	ds_read_b32 v11, v34 offset:1084
	ds_read_b32 v12, v35 offset:1084
	ds_read_b32 v13, v36 offset:1084
	v_mfma_f32_16x16x32_bf16 v[26:29], v[26:29], v[74:77], 0
	v_mfma_f32_16x16x32_bf16 v[30:33], v[30:33], v[74:77], 0
	v_mfma_f32_16x16x32_bf16 v[26:29], v[38:41], v[78:81], v[26:29]
	v_mfma_f32_16x16x32_bf16 v[30:33], v[42:45], v[78:81], v[30:33]
	s_nop 7
	v_cndmask_b32_e64 v26, v26, v30, s[4:5]
	s_waitcnt lgkmcnt(4)
; #define AT_LDK(KF, RSX, i) do { const LAS unsigned char* kb_ = lds + KRING_OFF + (((RSX) + (i)) % 9) * 8192 + kc0 * 128; \
;                         _Pragma("unroll") for (int cbk = 0; cbk < 2; ++cbk) { KF[cbk][0] = *(const LAS bf16x8*)(kb_ + cbk * 2048 + koff0); KF[cbk][1] = *(const LAS bf16x8*)(kb_ + cbk * 2048 + koff1); } } while (0)
; #define AT_MF(KF) do { _Pragma("unroll") for (int cbk = 0; cbk < 2; ++cbk) { cq[cbk] = (f32x4){0.f, 0.f, 0.f, 0.f}; \
;                         cq[cbk] = __builtin_amdgcn_mfma_f32_16x16x32_bf16(KF[cbk][0], qfn[0], cq[cbk], 0, 0, 0); cq[cbk] = __builtin_amdgcn_mfma_f32_16x16x32_bf16(KF[cbk][1], qfn[1], cq[cbk], 0, 0, 0); } } while (0)
; #define AT_SC(RK, BS, i) do { f32x4 s_; _Pragma("unroll") for (int e = 0; e < 4; ++e) s_[e] = (sel[e] ? cq[1][e] : cq[0][e]) * (sel[e] ? RK[1][e] : RK[0][e]) + BS[e]; \
;                         sc[i] = s_; mxn = fmaxf(fmaxf(mxn, fmaxf(s_[0], s_[1])), fmaxf(s_[2], s_[3])); } while (0)
; __global__ void __launch_bounds__(NWAVES * 64, 2) fwd(Args a) {
;     ...
;                         for (int i2 = 0; i2 < 3; ++i2) {
;                             AT_LDK(kB, rs, 2 * i2 + 1); AT_LDRB(rkvA, bsvA, rs, tba, 2 * i2); __builtin_amdgcn_sched_barrier(0);
;                             AT_MF(kA); __builtin_amdgcn_sched_barrier(0); AT_SC(rkvA, bsvA, 2 * i2); __builtin_amdgcn_sched_barrier(0);
;                             AT_LDK(kA, rs, 2 * i2 + 2); AT_LDRB(rkvA, bsvA, rs, tba, 2 * i2 + 1); __builtin_amdgcn_sched_barrier(0);
;                             AT_MF(kB); __builtin_amdgcn_sched_barrier(0); AT_SC(rkvA, bsvA, 2 * i2 + 1); __builtin_amdgcn_sched_barrier(0);
;                         }
;                         AT_LDRB(rkvA, bsvA, rs, tba, 6); __builtin_amdgcn_sched_barrier(0);
;                         AT_MF(kA); __builtin_amdgcn_sched_barrier(0); AT_SC(rkvA, bsvA, 6); __builtin_amdgcn_sched_barrier(0);
	v_cndmask_b32_e64 v14, v14, v54, s[4:5]
	s_waitcnt lgkmcnt(3)
	v_fmac_f32_e32 v10, v26, v14
	v_cndmask_b32_e64 v14, v27, v31, s[6:7]
	v_cndmask_b32_e64 v15, v15, v55, s[6:7]
	s_waitcnt lgkmcnt(2)
	v_fmac_f32_e32 v11, v14, v15
	v_cndmask_b32_e64 v14, v28, v32, s[8:9]
	v_cndmask_b32_e64 v15, v16, v56, s[8:9]
	s_waitcnt lgkmcnt(1)
	v_fmac_f32_e32 v12, v14, v15
	v_cndmask_b32_e64 v14, v29, v33, s[10:11]
	v_cndmask_b32_e64 v15, v17, v57, s[10:11]
	s_waitcnt lgkmcnt(0)
	v_fmac_f32_e32 v13, v14, v15
	v_max3_f32 v14, v37, s66, v58
	v_max_f32_e32 v15, v10, v11
	v_max_f32_e32 v16, v12, v13
	v_max3_f32 v37, v14, v15, v16
	s_or_b32 s70, s41, 3
	s_mul_hi_u32 s71, s70, 0x38e38e39
	s_lshr_b32 s71, s71, 1
	s_mul_i32 s71, s71, 9
	s_sub_i32 s70, s70, s71
	s_lshl_b32 s71, s70, 13
	s_add_i32 s71, s89, s71
	v_add_u32_e32 v14, s71, v169
	v_add_u32_e32 v15, s71, v170
	ds_read_b128 v[26:29], v14
	ds_read_b128 v[30:33], v14 offset:2048
	ds_read_b128 v[38:41], v15
	ds_read_b128 v[42:45], v15 offset:2048
	v_lshl_add_u32 v14, s28, 8, v175
	ds_read_b128 v[54:57], v14
	ds_read_b128 v[58:61], v14 offset:64
	ds_read_b32 v14, v2 offset:1212
	ds_read_b32 v15, v34 offset:1212
	ds_read_b32 v16, v35 offset:1212
	ds_read_b32 v17, v36 offset:1212
	v_mfma_f32_16x16x32_bf16 v[18:21], v[18:21], v[74:77], 0
	v_mfma_f32_16x16x32_bf16 v[22:25], v[22:25], v[74:77], 0
	v_mfma_f32_16x16x32_bf16 v[18:21], v[46:49], v[78:81], v[18:21]
	v_mfma_f32_16x16x32_bf16 v[22:25], v[50:53], v[78:81], v[22:25]
	s_nop 7
	v_cndmask_b32_e64 v18, v18, v22, s[4:5]
	s_waitcnt lgkmcnt(4)
	v_cndmask_b32_e64 v22, v54, v58, s[4:5]
	s_waitcnt lgkmcnt(3)
	v_fmac_f32_e32 v14, v18, v22
	v_cndmask_b32_e64 v18, v19, v23, s[6:7]
	v_cndmask_b32_e64 v19, v55, v59, s[6:7]
	s_waitcnt lgkmcnt(2)
	v_fmac_f32_e32 v15, v18, v19
	v_cndmask_b32_e64 v18, v20, v24, s[8:9]
	v_cndmask_b32_e64 v19, v56, v60, s[8:9]
	s_waitcnt lgkmcnt(1)
	v_fmac_f32_e32 v16, v18, v19
	v_cndmask_b32_e64 v18, v21, v25, s[10:11]
	v_cndmask_b32_e64 v19, v57, v61, s[10:11]
	s_waitcnt lgkmcnt(0)
	v_fmac_f32_e32 v17, v18, v19
	v_max_f32_e32 v82, v14, v15
	v_max_f32_e32 v83, v16, v17
	s_add_i32 s28, s41, 4
	s_mul_hi_u32 s71, s28, 0x38e38e39
	s_lshr_b32 s71, s71, 1
	s_mul_i32 s71, s71, 9
	s_sub_i32 s28, s28, s71
	s_lshl_b32 s71, s28, 13
	s_add_i32 s71, s89, s71
	v_add_u32_e32 v18, s71, v169
	v_add_u32_e32 v19, s71, v170
	ds_read_b128 v[46:49], v18
	ds_read_b128 v[50:53], v18 offset:2048
	ds_read_b128 v[54:57], v19
	ds_read_b128 v[58:61], v19 offset:2048
	v_lshl_add_u32 v18, s70, 8, v175
	ds_read_b128 v[22:25], v18
	ds_read_b128 v[62:65], v18 offset:64
	ds_read_b32 v18, v2 offset:1340
	ds_read_b32 v19, v34 offset:1340
	ds_read_b32 v20, v35 offset:1340
	ds_read_b32 v21, v36 offset:1340
	v_mfma_f32_16x16x32_bf16 v[26:29], v[26:29], v[74:77], 0
	v_mfma_f32_16x16x32_bf16 v[30:33], v[30:33], v[74:77], 0
	v_mfma_f32_16x16x32_bf16 v[26:29], v[38:41], v[78:81], v[26:29]
	v_mfma_f32_16x16x32_bf16 v[30:33], v[42:45], v[78:81], v[30:33]
	s_nop 7
	v_cndmask_b32_e64 v26, v26, v30, s[4:5]
	s_waitcnt lgkmcnt(4)
	v_cndmask_b32_e64 v22, v22, v62, s[4:5]
	s_waitcnt lgkmcnt(3)
	v_fmac_f32_e32 v18, v26, v22
	v_cndmask_b32_e64 v22, v27, v31, s[6:7]
	v_cndmask_b32_e64 v23, v23, v63, s[6:7]
	s_waitcnt lgkmcnt(2)
	v_fmac_f32_e32 v19, v22, v23
	v_cndmask_b32_e64 v22, v28, v32, s[8:9]
	v_cndmask_b32_e64 v23, v24, v64, s[8:9]
	s_waitcnt lgkmcnt(1)
	v_fmac_f32_e32 v20, v22, v23
	v_cndmask_b32_e64 v22, v29, v33, s[10:11]
	v_cndmask_b32_e64 v23, v25, v65, s[10:11]
	s_waitcnt lgkmcnt(0)
; #define AT_LDK(KF, RSX, i) do { const LAS unsigned char* kb_ = lds + KRING_OFF + (((RSX) + (i)) % 9) * 8192 + kc0 * 128; \
;                         _Pragma("unroll") for (int cbk = 0; cbk < 2; ++cbk) { KF[cbk][0] = *(const LAS bf16x8*)(kb_ + cbk * 2048 + koff0); KF[cbk][1] = *(const LAS bf16x8*)(kb_ + cbk * 2048 + koff1); } } while (0)
; #define AT_MF(KF) do { _Pragma("unroll") for (int cbk = 0; cbk < 2; ++cbk) { cq[cbk] = (f32x4){0.f, 0.f, 0.f, 0.f}; \
;                         cq[cbk] = __builtin_amdgcn_mfma_f32_16x16x32_bf16(KF[cbk][0], qfn[0], cq[cbk], 0, 0, 0); cq[cbk] = __builtin_amdgcn_mfma_f32_16x16x32_bf16(KF[cbk][1], qfn[1], cq[cbk], 0, 0, 0); } } while (0)
; #define AT_SC(RK, BS, i) do { f32x4 s_; _Pragma("unroll") for (int e = 0; e < 4; ++e) s_[e] = (sel[e] ? cq[1][e] : cq[0][e]) * (sel[e] ? RK[1][e] : RK[0][e]) + BS[e]; \
;                         sc[i] = s_; mxn = fmaxf(fmaxf(mxn, fmaxf(s_[0], s_[1])), fmaxf(s_[2], s_[3])); } while (0)
; __global__ void __launch_bounds__(NWAVES * 64, 2) fwd(Args a) {
;     ...
;                         for (int i2 = 0; i2 < 3; ++i2) {
;                             AT_LDK(kB, rs, 2 * i2 + 1); AT_LDRB(rkvA, bsvA, rs, tba, 2 * i2); __builtin_amdgcn_sched_barrier(0);
;                             AT_MF(kA); __builtin_amdgcn_sched_barrier(0); AT_SC(rkvA, bsvA, 2 * i2); __builtin_amdgcn_sched_barrier(0);
;                             AT_LDK(kA, rs, 2 * i2 + 2); AT_LDRB(rkvA, bsvA, rs, tba, 2 * i2 + 1); __builtin_amdgcn_sched_barrier(0);
;                             AT_MF(kB); __builtin_amdgcn_sched_barrier(0); AT_SC(rkvA, bsvA, 2 * i2 + 1); __builtin_amdgcn_sched_barrier(0);
;                         }
;                         AT_LDRB(rkvA, bsvA, rs, tba, 6); __builtin_amdgcn_sched_barrier(0);
;                         AT_MF(kA); __builtin_amdgcn_sched_barrier(0); AT_SC(rkvA, bsvA, 6); __builtin_amdgcn_sched_barrier(0);
;                     }
;                     AT_LDK(kA, rs, 7); AT_LDRB(rkvA, bsvA, rs, tba, 7); __builtin_amdgcn_sched_barrier(0);
;                     AT_MF(kA); __builtin_amdgcn_sched_barrier(0); AT_SC(rkvA, bsvA, 7); __builtin_amdgcn_sched_barrier(0);
	v_fmac_f32_e32 v21, v22, v23
	v_max3_f32 v22, v37, v82, v83
	v_max_f32_e32 v23, v18, v19
	v_max_f32_e32 v24, v20, v21
	v_max3_f32 v37, v22, v23, v24
	s_add_i32 s70, s41, 5
	s_mul_hi_u32 s71, s70, 0x38e38e39
	s_lshr_b32 s71, s71, 1
	s_mul_i32 s71, s71, 9
	s_sub_i32 s70, s70, s71
	s_lshl_b32 s71, s70, 13
	s_add_i32 s71, s89, s71
	v_add_u32_e32 v22, s71, v169
	v_add_u32_e32 v23, s71, v170
	ds_read_b128 v[30:33], v22
	ds_read_b128 v[38:41], v22 offset:2048
	ds_read_b128 v[42:45], v23
	ds_read_b128 v[62:65], v23 offset:2048
	v_lshl_add_u32 v22, s28, 8, v175
	ds_read_b128 v[26:29], v22
	ds_read_b128 v[82:85], v22 offset:64
	ds_read_b32 v22, v2 offset:1468
	ds_read_b32 v23, v34 offset:1468
	ds_read_b32 v24, v35 offset:1468
	ds_read_b32 v25, v36 offset:1468
	v_mfma_f32_16x16x32_bf16 v[46:49], v[46:49], v[74:77], 0
	v_mfma_f32_16x16x32_bf16 v[50:53], v[50:53], v[74:77], 0
	v_mfma_f32_16x16x32_bf16 v[46:49], v[54:57], v[78:81], v[46:49]
	v_mfma_f32_16x16x32_bf16 v[50:53], v[58:61], v[78:81], v[50:53]
	s_nop 7
	v_cndmask_b32_e64 v46, v46, v50, s[4:5]
	s_waitcnt lgkmcnt(4)
	v_cndmask_b32_e64 v26, v26, v82, s[4:5]
	s_waitcnt lgkmcnt(3)
	v_fmac_f32_e32 v22, v46, v26
	v_cndmask_b32_e64 v26, v47, v51, s[6:7]
	v_cndmask_b32_e64 v27, v27, v83, s[6:7]
	s_waitcnt lgkmcnt(2)
	v_fmac_f32_e32 v23, v26, v27
	v_cndmask_b32_e64 v26, v48, v52, s[8:9]
	v_cndmask_b32_e64 v27, v28, v84, s[8:9]
	s_waitcnt lgkmcnt(1)
	v_fmac_f32_e32 v24, v26, v27
	v_cndmask_b32_e64 v26, v49, v53, s[10:11]
	v_cndmask_b32_e64 v27, v29, v85, s[10:11]
	s_waitcnt lgkmcnt(0)
	v_fmac_f32_e32 v25, v26, v27
	v_max_f32_e32 v91, v22, v23
	v_max_f32_e32 v93, v24, v25
	s_add_i32 s28, s41, 6
	s_mul_hi_u32 s71, s28, 0x38e38e39
	s_lshr_b32 s71, s71, 1
	s_mul_i32 s71, s71, 9
	s_sub_i32 s28, s28, s71
	s_lshl_b32 s71, s28, 13
	s_add_i32 s71, s89, s71
	v_add_u32_e32 v26, s71, v169
	v_add_u32_e32 v27, s71, v170
	ds_read_b128 v[46:49], v26
	ds_read_b128 v[50:53], v26 offset:2048
	ds_read_b128 v[54:57], v27
	ds_read_b128 v[58:61], v27 offset:2048
	v_lshl_add_u32 v26, s70, 8, v175
	ds_read_b128 v[82:85], v26
	ds_read_b128 v[86:89], v26 offset:64
	ds_read_b32 v26, v2 offset:1596
	ds_read_b32 v27, v34 offset:1596
	ds_read_b32 v28, v35 offset:1596
	ds_read_b32 v29, v36 offset:1596
	v_mfma_f32_16x16x32_bf16 v[30:33], v[30:33], v[74:77], 0
	v_mfma_f32_16x16x32_bf16 v[30:33], v[42:45], v[78:81], v[30:33]
	v_mfma_f32_16x16x32_bf16 v[38:41], v[38:41], v[74:77], 0
	v_mfma_f32_16x16x32_bf16 v[38:41], v[62:65], v[78:81], v[38:41]
	s_nop 7
	v_cndmask_b32_e64 v30, v30, v38, s[4:5]
	s_waitcnt lgkmcnt(4)
	v_cndmask_b32_e64 v38, v82, v86, s[4:5]
	s_waitcnt lgkmcnt(3)
	v_fmac_f32_e32 v26, v30, v38
	v_cndmask_b32_e64 v30, v31, v39, s[6:7]
	v_cndmask_b32_e64 v31, v83, v87, s[6:7]
	s_waitcnt lgkmcnt(2)
	v_fmac_f32_e32 v27, v30, v31
	v_cndmask_b32_e64 v30, v32, v40, s[8:9]
	v_cndmask_b32_e64 v31, v84, v88, s[8:9]
	s_waitcnt lgkmcnt(1)
	v_fmac_f32_e32 v28, v30, v31
	v_cndmask_b32_e64 v30, v33, v41, s[10:11]
	v_cndmask_b32_e64 v31, v85, v89, s[10:11]
	s_waitcnt lgkmcnt(0)
	v_fmac_f32_e32 v29, v30, v31
	v_max_f32_e32 v62, v26, v27
	v_max_f32_e32 v63, v28, v29
	v_lshl_add_u32 v30, s28, 8, v175
	ds_read_b128 v[38:41], v30
	ds_read_b128 v[42:45], v30 offset:64
	ds_read_b32 v30, v2 offset:1724
	ds_read_b32 v31, v34 offset:1724
	ds_read_b32 v32, v35 offset:1724
	ds_read_b32 v33, v36 offset:1724
	v_mfma_f32_16x16x32_bf16 v[46:49], v[46:49], v[74:77], 0
	v_max3_f32 v37, v37, v91, v93
	v_mfma_f32_16x16x32_bf16 v[50:53], v[50:53], v[74:77], 0
	v_mfma_f32_16x16x32_bf16 v[46:49], v[54:57], v[78:81], v[46:49]
	v_mfma_f32_16x16x32_bf16 v[50:53], v[58:61], v[78:81], v[50:53]
	s_nop 7
	v_cndmask_b32_e64 v46, v46, v50, s[4:5]
	s_waitcnt lgkmcnt(4)
	v_cndmask_b32_e64 v38, v38, v42, s[4:5]
	s_waitcnt lgkmcnt(3)
	v_fmac_f32_e32 v30, v46, v38
	v_cndmask_b32_e64 v38, v47, v51, s[6:7]
	v_cndmask_b32_e64 v39, v39, v43, s[6:7]
	s_waitcnt lgkmcnt(2)
	v_fmac_f32_e32 v31, v38, v39
	v_cndmask_b32_e64 v38, v48, v52, s[8:9]
	v_cndmask_b32_e64 v39, v40, v44, s[8:9]
	s_waitcnt lgkmcnt(1)
	v_fmac_f32_e32 v32, v38, v39
	v_cndmask_b32_e64 v38, v49, v53, s[10:11]
	v_cndmask_b32_e64 v39, v41, v45, s[10:11]
	s_waitcnt lgkmcnt(0)
	v_fmac_f32_e32 v33, v38, v39
	v_max3_f32 v37, v37, v62, v63
	v_max_f32_e32 v38, v30, v31
	v_max_f32_e32 v39, v32, v33
	v_max3_f32 v195, v37, v38, v39

; __device__ __forceinline__ void xcd_barrier(const XcdBarrier& b) {
;     asm volatile("s_waitcnt vmcnt(0)" ::: "memory");
;     __syncthreads();
;     if (threadIdx.x == 0) {
;         unsigned* bar = b.bar;
;         __builtin_amdgcn_s_waitcnt(0);
;         unsigned nloc = b.st[0], nx = b.st[1];
;         if (nloc == 0u) { xcd_barrier_complete(bar, b.x, b.gsize, nloc, nx); b.st[0] = nloc; b.st[1] = nx; }
.LBB0_383:
	s_setprio 0
	s_waitcnt vmcnt(0)
	v_readlane_b32 s90, v250, 11
	v_readlane_b32 s91, v250, 12
	s_waitcnt vmcnt(0) lgkmcnt(0)
	s_barrier
	s_and_saveexec_b64 s[0:1], s[90:91]
	v_readlane_b32 s62, v250, 14
	s_mov_b32 s76, s67
	v_readlane_b32 s66, v250, 38
	v_readlane_b32 s89, v250, 13
	v_readlane_b32 s94, v250, 49
	v_readlane_b32 s95, v250, 48
	v_readlane_b32 s84, v250, 47
	v_readlane_b32 s85, v250, 46
	v_readlane_b32 s63, v250, 15
	v_readlane_b32 s77, v250, 45
	v_readlane_b32 s67, v250, 39
	v_readlane_b32 s60, v250, 44
	s_cbranch_execz .LBB0_435
	s_add_i32 s4, 0, 0x26170
	v_mov_b32_e32 v1, s4
	s_waitcnt vmcnt(0) expcnt(0) lgkmcnt(0)
	ds_read_b32 v3, v1
	s_add_i32 s4, 0, 0x26174
	v_mov_b32_e32 v1, s4
	ds_read_b32 v1, v1
	s_waitcnt lgkmcnt(1)
	v_cmp_ne_u32_e32 vcc, 0, v3
	s_cbranch_vccnz .LBB0_399
	s_add_u32 s4, s34, 0x1000
	s_addc_u32 s5, s35, 0
	s_add_u32 s6, s34, 0x1100
	s_addc_u32 s7, s35, 0
	s_add_u32 s8, s34, 0x1200
	s_addc_u32 s9, s35, 0
	s_add_u32 s10, s34, 0x1300
	s_addc_u32 s11, s35, 0
	s_mov_b32 s14, 1
	v_mov_b32_e32 v17, 0
	s_branch .LBB0_387
